# P0 x-row loop software-pipelined: two rows in flight per wave (next row's loads issued before this row's reduce/convert/stores)
# baseline (speedup 1.0000x reference)
.LBB0_248:
	s_or_b64 exec, exec, s[4:5]
	s_cmpk_gt_i32 s62, 0x1fff
	s_cbranch_scc1 .LBB0_253
	v_mbcnt_lo_u32_b32 v0, -1, 0
	v_mbcnt_hi_u32_b32 v0, -1, v0
	v_and_b32_e32 v1, 64, v0
	v_add_u32_e32 v1, 64, v1
	v_xor_b32_e32 v2, 1, v0
	v_cmp_lt_i32_e32 vcc, v2, v1
	s_ashr_i32 s63, s62, 31
	s_lshl_b64 s[4:5], s[62:63], 2
	v_cndmask_b32_e32 v2, v0, v2, vcc
	v_lshlrev_b32_e32 v38, 2, v2
	v_xor_b32_e32 v2, 2, v0
	v_cmp_lt_i32_e32 vcc, v2, v1
	s_add_u32 s3, s4, 0xfc04000
	s_waitcnt lgkmcnt(0)
	s_addc_u32 s20, s5, 0
	v_cndmask_b32_e32 v2, v0, v2, vcc
	v_lshlrev_b32_e32 v39, 2, v2
	v_xor_b32_e32 v2, 4, v0
	v_cmp_lt_i32_e32 vcc, v2, v1
	s_ashr_i32 s65, s64, 31
	s_lshl_b64 s[4:5], s[62:63], 12
	v_cndmask_b32_e32 v2, v0, v2, vcc
	v_lshlrev_b32_e32 v40, 2, v2
	v_xor_b32_e32 v2, 8, v0
	v_cmp_lt_i32_e32 vcc, v2, v1
	s_lshl_b64 s[10:11], s[64:65], 2
	v_lshl_or_b32 v32, v209, 3, s4
	v_cndmask_b32_e32 v2, v0, v2, vcc
	v_lshlrev_b32_e32 v41, 2, v2
	v_xor_b32_e32 v2, 16, v0
	v_cmp_lt_i32_e32 vcc, v2, v1
	v_mov_b32_e32 v33, s5
	s_lshl_b64 s[14:15], s[64:65], 12
	v_cndmask_b32_e32 v2, v0, v2, vcc
	v_lshlrev_b32_e32 v42, 2, v2
	v_xor_b32_e32 v2, 32, v0
	s_lshl_b64 s[4:5], s[62:63], 13
	v_cmp_lt_i32_e32 vcc, v2, v1
	s_add_u32 s4, s36, s4
	v_lshlrev_b32_e32 v34, 4, v209
	v_cndmask_b32_e32 v0, v0, v2, vcc
	v_mov_b32_e32 v35, 0
	s_addc_u32 s5, s37, s5
	v_lshlrev_b32_e32 v43, 2, v0
	v_lshl_add_u64 v[0:1], s[4:5], 0, v[34:35]
	s_mov_b64 s[4:5], 0x1000
	v_cmp_eq_u32_e64 s[0:1], 0, v209
	v_lshl_add_u64 v[36:37], v[0:1], 0, s[4:5]
	s_lshl_b64 s[16:17], s[64:65], 13
	v_mov_b32_e32 v34, 0x358637bd
	s_mov_b32 s21, 0xf800000
	v_mov_b32_e32 v44, 0x260
	s_movk_i32 s36, 0x7fff
	s_mov_b32 s37, 0xffff0000
	s_cmpk_lg_u32 s64, 0x800
	s_cbranch_scc1 .LBB0_251
	global_load_dwordx4 v[28:31], v[36:37], off offset:-4096 nt
	global_load_dwordx4 v[24:27], v[36:37], off offset:-3072 nt
	global_load_dwordx4 v[20:23], v[36:37], off offset:-2048 nt
	global_load_dwordx4 v[16:19], v[36:37], off offset:-1024 nt
	global_load_dwordx4 v[12:15], v[36:37], off nt
	global_load_dwordx4 v[8:11], v[36:37], off offset:1024 nt
	global_load_dwordx4 v[4:7], v[36:37], off offset:2048 nt
	global_load_dwordx4 v[0:3], v[36:37], off offset:3072 nt
	v_lshl_add_u64 v[36:37], v[36:37], 0, s[16:17]
	global_load_dwordx4 v[92:95], v[36:37], off offset:-4096 nt
	global_load_dwordx4 v[88:91], v[36:37], off offset:-3072 nt
	global_load_dwordx4 v[84:87], v[36:37], off offset:-2048 nt
	global_load_dwordx4 v[80:83], v[36:37], off offset:-1024 nt
	global_load_dwordx4 v[76:79], v[36:37], off nt
	global_load_dwordx4 v[72:75], v[36:37], off offset:1024 nt
	global_load_dwordx4 v[68:71], v[36:37], off offset:2048 nt
	global_load_dwordx4 v[64:67], v[36:37], off offset:3072 nt
	v_lshl_add_u64 v[36:37], v[36:37], 0, s[16:17]
	s_waitcnt vmcnt(8)
	v_mul_f32_e32 v45, v29, v29
	v_mul_f32_e32 v46, v31, v31
	v_mul_f32_e32 v47, v25, v25
	v_mul_f32_e32 v48, v27, v27
	v_mul_f32_e32 v49, v21, v21
	v_mul_f32_e32 v50, v23, v23
	v_fmac_f32_e32 v45, v28, v28
	v_fmac_f32_e32 v46, v30, v30
	v_fmac_f32_e32 v47, v24, v24
	v_fmac_f32_e32 v48, v26, v26
	v_mul_f32_e32 v51, v17, v17
	v_mul_f32_e32 v52, v19, v19
	v_fmac_f32_e32 v49, v20, v20
	v_fmac_f32_e32 v50, v22, v22
	v_add_f32_e32 v45, v45, v46
	v_add_f32_e32 v46, v47, v48
	v_mul_f32_e32 v53, v13, v13
	v_mul_f32_e32 v54, v15, v15
	v_fmac_f32_e32 v51, v16, v16
	v_fmac_f32_e32 v52, v18, v18
	v_add_f32_e32 v47, v49, v50
	v_add_f32_e32 v45, v45, v46
	v_mul_f32_e32 v55, v9, v9
	v_mul_f32_e32 v56, v11, v11
	v_fmac_f32_e32 v53, v12, v12
	v_fmac_f32_e32 v54, v14, v14
	v_add_f32_e32 v48, v51, v52
	v_add_f32_e32 v45, v45, v47
	v_mul_f32_e32 v57, v5, v5
	v_mul_f32_e32 v58, v7, v7
	v_fmac_f32_e32 v55, v8, v8
	v_fmac_f32_e32 v56, v10, v10
	v_add_f32_e32 v49, v53, v54
	v_add_f32_e32 v45, v45, v48
	v_mul_f32_e32 v59, v1, v1
	v_mul_f32_e32 v60, v3, v3
	v_fmac_f32_e32 v57, v4, v4
	v_fmac_f32_e32 v58, v6, v6
	v_add_f32_e32 v50, v55, v56
	v_add_f32_e32 v45, v45, v49
	v_fmac_f32_e32 v59, v0, v0
	v_fmac_f32_e32 v60, v2, v2
	v_add_f32_e32 v51, v57, v58
	v_add_f32_e32 v45, v45, v50
	v_add_f32_e32 v45, v45, v51
	v_add_f32_e32 v46, v59, v60
	v_add_f32_e32 v45, v45, v46
	ds_bpermute_b32 v46, v38, v45
	s_waitcnt lgkmcnt(0)
	v_add_f32_e32 v45, v45, v46
	ds_bpermute_b32 v46, v39, v45
	s_waitcnt lgkmcnt(0)
	v_add_f32_e32 v45, v45, v46
	ds_bpermute_b32 v46, v40, v45
	s_waitcnt lgkmcnt(0)
	v_add_f32_e32 v45, v45, v46
	ds_bpermute_b32 v46, v41, v45
	s_waitcnt lgkmcnt(0)
	v_add_f32_e32 v45, v45, v46
	ds_bpermute_b32 v46, v42, v45
	s_waitcnt lgkmcnt(0)
	v_add_f32_e32 v45, v45, v46
	ds_bpermute_b32 v46, v43, v45
	s_and_saveexec_b64 s[18:19], s[0:1]
	s_cbranch_execz .Lmy_xp_r0
	s_waitcnt lgkmcnt(0)
	v_add_f32_e32 v45, v45, v46
	v_fmamk_f32 v45, v45, 0x3a000000, v34
	v_mul_f32_e32 v46, 0x4f800000, v45
	v_cmp_gt_f32_e32 vcc, s21, v45
	s_nop 1
	v_cndmask_b32_e32 v45, v45, v46, vcc
	v_sqrt_f32_e32 v46, v45
	s_nop 0
	v_add_u32_e32 v47, -1, v46
	v_fma_f32 v49, -v47, v46, v45
	v_add_u32_e32 v48, 1, v46
	v_cmp_ge_f32_e64 s[4:5], 0, v49
	s_nop 1
	v_cndmask_b32_e64 v47, v46, v47, s[4:5]
	v_fma_f32 v46, -v48, v46, v45
	v_cmp_lt_f32_e64 s[4:5], 0, v46
	s_nop 1
	v_cndmask_b32_e64 v46, v47, v48, s[4:5]
	v_mul_f32_e32 v47, 0x37800000, v46
	v_cndmask_b32_e32 v46, v46, v47, vcc
	v_cmp_class_f32_e32 vcc, v45, v44
	s_nop 1
	v_cndmask_b32_e32 v45, v46, v45, vcc
	v_div_scale_f32 v46, s[4:5], v45, v45, 1.0
	v_rcp_f32_e32 v47, v46
	s_add_u32 s4, s26, s3
	s_addc_u32 s5, s27, s20
	v_fma_f32 v48, -v46, v47, 1.0
	v_fmac_f32_e32 v47, v48, v47
	v_div_scale_f32 v48, vcc, 1.0, v45, 1.0
	v_mul_f32_e32 v49, v48, v47
	v_fma_f32 v50, -v46, v49, v48
	v_fmac_f32_e32 v49, v50, v47
	v_fma_f32 v46, -v46, v49, v48
	v_div_fmas_f32 v46, v46, v47, v49
	v_div_fixup_f32 v45, v46, v45, 1.0
	global_store_dword v35, v45, s[4:5]
.Lmy_xp_r0:
	s_or_b64 exec, exec, s[18:19]
	v_bfe_u32 v45, v28, 16, 1
	v_add3_u32 v28, v28, v45, s36
	v_bfe_u32 v45, v29, 16, 1
	v_lshrrev_b32_e32 v28, 16, v28
	v_add3_u32 v29, v29, v45, s36
	v_and_or_b32 v28, v29, s37, v28
	v_bfe_u32 v29, v30, 16, 1
	v_add3_u32 v29, v30, v29, s36
	v_bfe_u32 v30, v31, 16, 1
	s_waitcnt lgkmcnt(0)
	v_lshl_add_u64 v[46:47], s[26:27], 0, v[32:33]
	v_lshrrev_b32_e32 v29, 16, v29
	v_add3_u32 v30, v31, v30, s36
	v_and_or_b32 v29, v30, s37, v29
	v_add_co_u32_e32 v30, vcc, 0x6400000, v46
	s_add_i32 s62, s62, s64
	s_nop 0
	v_addc_co_u32_e32 v31, vcc, 0, v47, vcc
	global_store_dwordx2 v[30:31], v[28:29], off
	v_bfe_u32 v28, v24, 16, 1
	v_add3_u32 v24, v24, v28, s36
	v_bfe_u32 v28, v25, 16, 1
	v_lshrrev_b32_e32 v24, 16, v24
	v_add3_u32 v25, v25, v28, s36
	v_and_or_b32 v24, v25, s37, v24
	v_bfe_u32 v25, v26, 16, 1
	v_add3_u32 v25, v26, v25, s36
	v_bfe_u32 v26, v27, 16, 1
	v_lshrrev_b32_e32 v25, 16, v25
	v_add3_u32 v26, v27, v26, s36
	v_and_or_b32 v25, v26, s37, v25
	global_store_dwordx2 v[30:31], v[24:25], off offset:512
	v_bfe_u32 v24, v20, 16, 1
	v_add3_u32 v20, v20, v24, s36
	v_bfe_u32 v24, v21, 16, 1
	v_lshrrev_b32_e32 v20, 16, v20
	v_add3_u32 v21, v21, v24, s36
	v_and_or_b32 v20, v21, s37, v20
	v_bfe_u32 v21, v22, 16, 1
	v_add3_u32 v21, v22, v21, s36
	v_bfe_u32 v22, v23, 16, 1
	v_lshrrev_b32_e32 v21, 16, v21
	v_add3_u32 v22, v23, v22, s36
	v_and_or_b32 v21, v22, s37, v21
	global_store_dwordx2 v[30:31], v[20:21], off offset:1024
	v_bfe_u32 v20, v16, 16, 1
	v_add3_u32 v16, v16, v20, s36
	v_bfe_u32 v20, v17, 16, 1
	v_lshrrev_b32_e32 v16, 16, v16
	v_add3_u32 v17, v17, v20, s36
	v_and_or_b32 v16, v17, s37, v16
	v_bfe_u32 v17, v18, 16, 1
	v_add3_u32 v17, v18, v17, s36
	v_bfe_u32 v18, v19, 16, 1
	v_lshrrev_b32_e32 v17, 16, v17
	v_add3_u32 v18, v19, v18, s36
	v_and_or_b32 v17, v18, s37, v17
	global_store_dwordx2 v[30:31], v[16:17], off offset:1536
	v_bfe_u32 v16, v12, 16, 1
	v_add3_u32 v12, v12, v16, s36
	v_bfe_u32 v16, v13, 16, 1
	v_lshrrev_b32_e32 v12, 16, v12
	v_add3_u32 v13, v13, v16, s36
	v_and_or_b32 v12, v13, s37, v12
	v_bfe_u32 v13, v14, 16, 1
	v_add3_u32 v13, v14, v13, s36
	v_bfe_u32 v14, v15, 16, 1
	v_lshrrev_b32_e32 v13, 16, v13
	v_add3_u32 v14, v15, v14, s36
	v_and_or_b32 v13, v14, s37, v13
	global_store_dwordx2 v[30:31], v[12:13], off offset:2048
	v_bfe_u32 v12, v8, 16, 1
	v_add3_u32 v8, v8, v12, s36
	v_bfe_u32 v12, v9, 16, 1
	v_lshrrev_b32_e32 v8, 16, v8
	v_add3_u32 v9, v9, v12, s36
	v_and_or_b32 v8, v9, s37, v8
	v_bfe_u32 v9, v10, 16, 1
	v_add3_u32 v9, v10, v9, s36
	v_bfe_u32 v10, v11, 16, 1
	v_lshrrev_b32_e32 v9, 16, v9
	v_add3_u32 v10, v11, v10, s36
	v_and_or_b32 v9, v10, s37, v9
	global_store_dwordx2 v[30:31], v[8:9], off offset:2560
	v_bfe_u32 v8, v4, 16, 1
	v_add3_u32 v4, v4, v8, s36
	v_bfe_u32 v8, v5, 16, 1
	v_lshrrev_b32_e32 v4, 16, v4
	v_add3_u32 v5, v5, v8, s36
	v_and_or_b32 v4, v5, s37, v4
	v_bfe_u32 v5, v6, 16, 1
	v_add3_u32 v5, v6, v5, s36
	v_bfe_u32 v6, v7, 16, 1
	v_lshrrev_b32_e32 v5, 16, v5
	v_add3_u32 v6, v7, v6, s36
	v_and_or_b32 v5, v6, s37, v5
	global_store_dwordx2 v[30:31], v[4:5], off offset:3072
	v_bfe_u32 v4, v0, 16, 1
	v_add3_u32 v0, v0, v4, s36
	v_bfe_u32 v4, v1, 16, 1
	v_lshrrev_b32_e32 v0, 16, v0
	v_add3_u32 v1, v1, v4, s36
	v_and_or_b32 v0, v1, s37, v0
	v_bfe_u32 v1, v2, 16, 1
	v_add3_u32 v1, v2, v1, s36
	v_bfe_u32 v2, v3, 16, 1
	s_add_u32 s3, s3, s10
	v_lshrrev_b32_e32 v1, 16, v1
	v_add3_u32 v2, v3, v2, s36
	s_addc_u32 s20, s20, s11
	v_and_or_b32 v1, v2, s37, v1
	v_lshl_add_u64 v[32:33], v[32:33], 0, s[14:15]
	global_store_dwordx2 v[30:31], v[0:1], off offset:3584
	global_load_dwordx4 v[28:31], v[36:37], off offset:-4096 nt
	global_load_dwordx4 v[24:27], v[36:37], off offset:-3072 nt
	global_load_dwordx4 v[20:23], v[36:37], off offset:-2048 nt
	global_load_dwordx4 v[16:19], v[36:37], off offset:-1024 nt
	global_load_dwordx4 v[12:15], v[36:37], off nt
	global_load_dwordx4 v[8:11], v[36:37], off offset:1024 nt
	global_load_dwordx4 v[4:7], v[36:37], off offset:2048 nt
	global_load_dwordx4 v[0:3], v[36:37], off offset:3072 nt
	v_lshl_add_u64 v[36:37], v[36:37], 0, s[16:17]
	s_waitcnt vmcnt(17)
	v_mul_f32_e32 v45, v93, v93
	v_mul_f32_e32 v46, v95, v95
	v_mul_f32_e32 v47, v89, v89
	v_mul_f32_e32 v48, v91, v91
	v_mul_f32_e32 v49, v85, v85
	v_mul_f32_e32 v50, v87, v87
	v_fmac_f32_e32 v45, v92, v92
	v_fmac_f32_e32 v46, v94, v94
	v_fmac_f32_e32 v47, v88, v88
	v_fmac_f32_e32 v48, v90, v90
	v_mul_f32_e32 v51, v81, v81
	v_mul_f32_e32 v52, v83, v83
	v_fmac_f32_e32 v49, v84, v84
	v_fmac_f32_e32 v50, v86, v86
	v_add_f32_e32 v45, v45, v46
	v_add_f32_e32 v46, v47, v48
	v_mul_f32_e32 v53, v77, v77
	v_mul_f32_e32 v54, v79, v79
	v_fmac_f32_e32 v51, v80, v80
	v_fmac_f32_e32 v52, v82, v82
	v_add_f32_e32 v47, v49, v50
	v_add_f32_e32 v45, v45, v46
	v_mul_f32_e32 v55, v73, v73
	v_mul_f32_e32 v56, v75, v75
	v_fmac_f32_e32 v53, v76, v76
	v_fmac_f32_e32 v54, v78, v78
	v_add_f32_e32 v48, v51, v52
	v_add_f32_e32 v45, v45, v47
	v_mul_f32_e32 v57, v69, v69
	v_mul_f32_e32 v58, v71, v71
	v_fmac_f32_e32 v55, v72, v72
	v_fmac_f32_e32 v56, v74, v74
	v_add_f32_e32 v49, v53, v54
	v_add_f32_e32 v45, v45, v48
	v_mul_f32_e32 v59, v65, v65
	v_mul_f32_e32 v60, v67, v67
	v_fmac_f32_e32 v57, v68, v68
	v_fmac_f32_e32 v58, v70, v70
	v_add_f32_e32 v50, v55, v56
	v_add_f32_e32 v45, v45, v49
	v_fmac_f32_e32 v59, v64, v64
	v_fmac_f32_e32 v60, v66, v66
	v_add_f32_e32 v51, v57, v58
	v_add_f32_e32 v45, v45, v50
	v_add_f32_e32 v45, v45, v51
	v_add_f32_e32 v46, v59, v60
	v_add_f32_e32 v45, v45, v46
	ds_bpermute_b32 v46, v38, v45
	s_waitcnt lgkmcnt(0)
	v_add_f32_e32 v45, v45, v46
	ds_bpermute_b32 v46, v39, v45
	s_waitcnt lgkmcnt(0)
	v_add_f32_e32 v45, v45, v46
	ds_bpermute_b32 v46, v40, v45
	s_waitcnt lgkmcnt(0)
	v_add_f32_e32 v45, v45, v46
	ds_bpermute_b32 v46, v41, v45
	s_waitcnt lgkmcnt(0)
	v_add_f32_e32 v45, v45, v46
	ds_bpermute_b32 v46, v42, v45
	s_waitcnt lgkmcnt(0)
	v_add_f32_e32 v45, v45, v46
	ds_bpermute_b32 v46, v43, v45
	s_and_saveexec_b64 s[18:19], s[0:1]
	s_cbranch_execz .Lmy_xp_r1
	s_waitcnt lgkmcnt(0)
	v_add_f32_e32 v45, v45, v46
	v_fmamk_f32 v45, v45, 0x3a000000, v34
	v_mul_f32_e32 v46, 0x4f800000, v45
	v_cmp_gt_f32_e32 vcc, s21, v45
	s_nop 1
	v_cndmask_b32_e32 v45, v45, v46, vcc
	v_sqrt_f32_e32 v46, v45
	s_nop 0
	v_add_u32_e32 v47, -1, v46
	v_fma_f32 v49, -v47, v46, v45
	v_add_u32_e32 v48, 1, v46
	v_cmp_ge_f32_e64 s[4:5], 0, v49
	s_nop 1
	v_cndmask_b32_e64 v47, v46, v47, s[4:5]
	v_fma_f32 v46, -v48, v46, v45
	v_cmp_lt_f32_e64 s[4:5], 0, v46
	s_nop 1
	v_cndmask_b32_e64 v46, v47, v48, s[4:5]
	v_mul_f32_e32 v47, 0x37800000, v46
	v_cndmask_b32_e32 v46, v46, v47, vcc
	v_cmp_class_f32_e32 vcc, v45, v44
	s_nop 1
	v_cndmask_b32_e32 v45, v46, v45, vcc
	v_div_scale_f32 v46, s[4:5], v45, v45, 1.0
	v_rcp_f32_e32 v47, v46
	s_add_u32 s4, s26, s3
	s_addc_u32 s5, s27, s20
	v_fma_f32 v48, -v46, v47, 1.0
	v_fmac_f32_e32 v47, v48, v47
	v_div_scale_f32 v48, vcc, 1.0, v45, 1.0
	v_mul_f32_e32 v49, v48, v47
	v_fma_f32 v50, -v46, v49, v48
	v_fmac_f32_e32 v49, v50, v47
	v_fma_f32 v46, -v46, v49, v48
	v_div_fmas_f32 v46, v46, v47, v49
	v_div_fixup_f32 v45, v46, v45, 1.0
	global_store_dword v35, v45, s[4:5]
.Lmy_xp_r1:
	s_or_b64 exec, exec, s[18:19]
	v_bfe_u32 v45, v92, 16, 1
	v_add3_u32 v92, v92, v45, s36
	v_bfe_u32 v45, v93, 16, 1
	v_lshrrev_b32_e32 v92, 16, v92
	v_add3_u32 v93, v93, v45, s36
	v_and_or_b32 v92, v93, s37, v92
	v_bfe_u32 v93, v94, 16, 1
	v_add3_u32 v93, v94, v93, s36
	v_bfe_u32 v94, v95, 16, 1
	s_waitcnt lgkmcnt(0)
	v_lshl_add_u64 v[46:47], s[26:27], 0, v[32:33]
	v_lshrrev_b32_e32 v93, 16, v93
	v_add3_u32 v94, v95, v94, s36
	v_and_or_b32 v93, v94, s37, v93
	v_add_co_u32_e32 v94, vcc, 0x6400000, v46
	s_add_i32 s62, s62, s64
	s_nop 0
	v_addc_co_u32_e32 v95, vcc, 0, v47, vcc
	global_store_dwordx2 v[94:95], v[92:93], off
	v_bfe_u32 v92, v88, 16, 1
	v_add3_u32 v88, v88, v92, s36
	v_bfe_u32 v92, v89, 16, 1
	v_lshrrev_b32_e32 v88, 16, v88
	v_add3_u32 v89, v89, v92, s36
	v_and_or_b32 v88, v89, s37, v88
	v_bfe_u32 v89, v90, 16, 1
	v_add3_u32 v89, v90, v89, s36
	v_bfe_u32 v90, v91, 16, 1
	v_lshrrev_b32_e32 v89, 16, v89
	v_add3_u32 v90, v91, v90, s36
	v_and_or_b32 v89, v90, s37, v89
	global_store_dwordx2 v[94:95], v[88:89], off offset:512
	v_bfe_u32 v88, v84, 16, 1
	v_add3_u32 v84, v84, v88, s36
	v_bfe_u32 v88, v85, 16, 1
	v_lshrrev_b32_e32 v84, 16, v84
	v_add3_u32 v85, v85, v88, s36
	v_and_or_b32 v84, v85, s37, v84
	v_bfe_u32 v85, v86, 16, 1
	v_add3_u32 v85, v86, v85, s36
	v_bfe_u32 v86, v87, 16, 1
	v_lshrrev_b32_e32 v85, 16, v85
	v_add3_u32 v86, v87, v86, s36
	v_and_or_b32 v85, v86, s37, v85
	global_store_dwordx2 v[94:95], v[84:85], off offset:1024
	v_bfe_u32 v84, v80, 16, 1
	v_add3_u32 v80, v80, v84, s36
	v_bfe_u32 v84, v81, 16, 1
	v_lshrrev_b32_e32 v80, 16, v80
	v_add3_u32 v81, v81, v84, s36
	v_and_or_b32 v80, v81, s37, v80
	v_bfe_u32 v81, v82, 16, 1
	v_add3_u32 v81, v82, v81, s36
	v_bfe_u32 v82, v83, 16, 1
	v_lshrrev_b32_e32 v81, 16, v81
	v_add3_u32 v82, v83, v82, s36
	v_and_or_b32 v81, v82, s37, v81
	global_store_dwordx2 v[94:95], v[80:81], off offset:1536
	v_bfe_u32 v80, v76, 16, 1
	v_add3_u32 v76, v76, v80, s36
	v_bfe_u32 v80, v77, 16, 1
	v_lshrrev_b32_e32 v76, 16, v76
	v_add3_u32 v77, v77, v80, s36
	v_and_or_b32 v76, v77, s37, v76
	v_bfe_u32 v77, v78, 16, 1
	v_add3_u32 v77, v78, v77, s36
	v_bfe_u32 v78, v79, 16, 1
	v_lshrrev_b32_e32 v77, 16, v77
	v_add3_u32 v78, v79, v78, s36
	v_and_or_b32 v77, v78, s37, v77
	global_store_dwordx2 v[94:95], v[76:77], off offset:2048
	v_bfe_u32 v76, v72, 16, 1
	v_add3_u32 v72, v72, v76, s36
	v_bfe_u32 v76, v73, 16, 1
	v_lshrrev_b32_e32 v72, 16, v72
	v_add3_u32 v73, v73, v76, s36
	v_and_or_b32 v72, v73, s37, v72
	v_bfe_u32 v73, v74, 16, 1
	v_add3_u32 v73, v74, v73, s36
	v_bfe_u32 v74, v75, 16, 1
	v_lshrrev_b32_e32 v73, 16, v73
	v_add3_u32 v74, v75, v74, s36
	v_and_or_b32 v73, v74, s37, v73
	global_store_dwordx2 v[94:95], v[72:73], off offset:2560
	v_bfe_u32 v72, v68, 16, 1
	v_add3_u32 v68, v68, v72, s36
	v_bfe_u32 v72, v69, 16, 1
	v_lshrrev_b32_e32 v68, 16, v68
	v_add3_u32 v69, v69, v72, s36
	v_and_or_b32 v68, v69, s37, v68
	v_bfe_u32 v69, v70, 16, 1
	v_add3_u32 v69, v70, v69, s36
	v_bfe_u32 v70, v71, 16, 1
	v_lshrrev_b32_e32 v69, 16, v69
	v_add3_u32 v70, v71, v70, s36
	v_and_or_b32 v69, v70, s37, v69
	global_store_dwordx2 v[94:95], v[68:69], off offset:3072
	v_bfe_u32 v68, v64, 16, 1
	v_add3_u32 v64, v64, v68, s36
	v_bfe_u32 v68, v65, 16, 1
	v_lshrrev_b32_e32 v64, 16, v64
	v_add3_u32 v65, v65, v68, s36
	v_and_or_b32 v64, v65, s37, v64
	v_bfe_u32 v65, v66, 16, 1
	v_add3_u32 v65, v66, v65, s36
	v_bfe_u32 v66, v67, 16, 1
	s_add_u32 s3, s3, s10
	v_lshrrev_b32_e32 v65, 16, v65
	v_add3_u32 v66, v67, v66, s36
	s_addc_u32 s20, s20, s11
	v_and_or_b32 v65, v66, s37, v65
	v_lshl_add_u64 v[32:33], v[32:33], 0, s[14:15]
	global_store_dwordx2 v[94:95], v[64:65], off offset:3584
	global_load_dwordx4 v[92:95], v[36:37], off offset:-4096 nt
	global_load_dwordx4 v[88:91], v[36:37], off offset:-3072 nt
	global_load_dwordx4 v[84:87], v[36:37], off offset:-2048 nt
	global_load_dwordx4 v[80:83], v[36:37], off offset:-1024 nt
	global_load_dwordx4 v[76:79], v[36:37], off nt
	global_load_dwordx4 v[72:75], v[36:37], off offset:1024 nt
	global_load_dwordx4 v[68:71], v[36:37], off offset:2048 nt
	global_load_dwordx4 v[64:67], v[36:37], off offset:3072 nt
	v_lshl_add_u64 v[36:37], v[36:37], 0, s[16:17]
	s_waitcnt vmcnt(17)
	v_mul_f32_e32 v45, v29, v29
	v_mul_f32_e32 v46, v31, v31
	v_mul_f32_e32 v47, v25, v25
	v_mul_f32_e32 v48, v27, v27
	v_mul_f32_e32 v49, v21, v21
	v_mul_f32_e32 v50, v23, v23
	v_fmac_f32_e32 v45, v28, v28
	v_fmac_f32_e32 v46, v30, v30
	v_fmac_f32_e32 v47, v24, v24
	v_fmac_f32_e32 v48, v26, v26
	v_mul_f32_e32 v51, v17, v17
	v_mul_f32_e32 v52, v19, v19
	v_fmac_f32_e32 v49, v20, v20
	v_fmac_f32_e32 v50, v22, v22
	v_add_f32_e32 v45, v45, v46
	v_add_f32_e32 v46, v47, v48
	v_mul_f32_e32 v53, v13, v13
	v_mul_f32_e32 v54, v15, v15
	v_fmac_f32_e32 v51, v16, v16
	v_fmac_f32_e32 v52, v18, v18
	v_add_f32_e32 v47, v49, v50
	v_add_f32_e32 v45, v45, v46
	v_mul_f32_e32 v55, v9, v9
	v_mul_f32_e32 v56, v11, v11
	v_fmac_f32_e32 v53, v12, v12
	v_fmac_f32_e32 v54, v14, v14
	v_add_f32_e32 v48, v51, v52
	v_add_f32_e32 v45, v45, v47
	v_mul_f32_e32 v57, v5, v5
	v_mul_f32_e32 v58, v7, v7
	v_fmac_f32_e32 v55, v8, v8
	v_fmac_f32_e32 v56, v10, v10
	v_add_f32_e32 v49, v53, v54
	v_add_f32_e32 v45, v45, v48
	v_mul_f32_e32 v59, v1, v1
	v_mul_f32_e32 v60, v3, v3
	v_fmac_f32_e32 v57, v4, v4
	v_fmac_f32_e32 v58, v6, v6
	v_add_f32_e32 v50, v55, v56
	v_add_f32_e32 v45, v45, v49
	v_fmac_f32_e32 v59, v0, v0
	v_fmac_f32_e32 v60, v2, v2
	v_add_f32_e32 v51, v57, v58
	v_add_f32_e32 v45, v45, v50
	v_add_f32_e32 v45, v45, v51
	v_add_f32_e32 v46, v59, v60
	v_add_f32_e32 v45, v45, v46
	ds_bpermute_b32 v46, v38, v45
	s_waitcnt lgkmcnt(0)
	v_add_f32_e32 v45, v45, v46
	ds_bpermute_b32 v46, v39, v45
	s_waitcnt lgkmcnt(0)
	v_add_f32_e32 v45, v45, v46
	ds_bpermute_b32 v46, v40, v45
	s_waitcnt lgkmcnt(0)
	v_add_f32_e32 v45, v45, v46
	ds_bpermute_b32 v46, v41, v45
	s_waitcnt lgkmcnt(0)
	v_add_f32_e32 v45, v45, v46
	ds_bpermute_b32 v46, v42, v45
	s_waitcnt lgkmcnt(0)
	v_add_f32_e32 v45, v45, v46
	ds_bpermute_b32 v46, v43, v45
	s_and_saveexec_b64 s[18:19], s[0:1]
	s_cbranch_execz .Lmy_xp_r2
	s_waitcnt lgkmcnt(0)
	v_add_f32_e32 v45, v45, v46
	v_fmamk_f32 v45, v45, 0x3a000000, v34
	v_mul_f32_e32 v46, 0x4f800000, v45
	v_cmp_gt_f32_e32 vcc, s21, v45
	s_nop 1
	v_cndmask_b32_e32 v45, v45, v46, vcc
	v_sqrt_f32_e32 v46, v45
	s_nop 0
	v_add_u32_e32 v47, -1, v46
	v_fma_f32 v49, -v47, v46, v45
	v_add_u32_e32 v48, 1, v46
	v_cmp_ge_f32_e64 s[4:5], 0, v49
	s_nop 1
	v_cndmask_b32_e64 v47, v46, v47, s[4:5]
	v_fma_f32 v46, -v48, v46, v45
	v_cmp_lt_f32_e64 s[4:5], 0, v46
	s_nop 1
	v_cndmask_b32_e64 v46, v47, v48, s[4:5]
	v_mul_f32_e32 v47, 0x37800000, v46
	v_cndmask_b32_e32 v46, v46, v47, vcc
	v_cmp_class_f32_e32 vcc, v45, v44
	s_nop 1
	v_cndmask_b32_e32 v45, v46, v45, vcc
	v_div_scale_f32 v46, s[4:5], v45, v45, 1.0
	v_rcp_f32_e32 v47, v46
	s_add_u32 s4, s26, s3
	s_addc_u32 s5, s27, s20
	v_fma_f32 v48, -v46, v47, 1.0
	v_fmac_f32_e32 v47, v48, v47
	v_div_scale_f32 v48, vcc, 1.0, v45, 1.0
	v_mul_f32_e32 v49, v48, v47
	v_fma_f32 v50, -v46, v49, v48
	v_fmac_f32_e32 v49, v50, v47
	v_fma_f32 v46, -v46, v49, v48
	v_div_fmas_f32 v46, v46, v47, v49
	v_div_fixup_f32 v45, v46, v45, 1.0
	global_store_dword v35, v45, s[4:5]
.Lmy_xp_r2:
	s_or_b64 exec, exec, s[18:19]
	v_bfe_u32 v45, v28, 16, 1
	v_add3_u32 v28, v28, v45, s36
	v_bfe_u32 v45, v29, 16, 1
	v_lshrrev_b32_e32 v28, 16, v28
	v_add3_u32 v29, v29, v45, s36
	v_and_or_b32 v28, v29, s37, v28
	v_bfe_u32 v29, v30, 16, 1
	v_add3_u32 v29, v30, v29, s36
	v_bfe_u32 v30, v31, 16, 1
	s_waitcnt lgkmcnt(0)
	v_lshl_add_u64 v[46:47], s[26:27], 0, v[32:33]
	v_lshrrev_b32_e32 v29, 16, v29
	v_add3_u32 v30, v31, v30, s36
	v_and_or_b32 v29, v30, s37, v29
	v_add_co_u32_e32 v30, vcc, 0x6400000, v46
	s_add_i32 s62, s62, s64
	s_nop 0
	v_addc_co_u32_e32 v31, vcc, 0, v47, vcc
	global_store_dwordx2 v[30:31], v[28:29], off
	v_bfe_u32 v28, v24, 16, 1
	v_add3_u32 v24, v24, v28, s36
	v_bfe_u32 v28, v25, 16, 1
	v_lshrrev_b32_e32 v24, 16, v24
	v_add3_u32 v25, v25, v28, s36
	v_and_or_b32 v24, v25, s37, v24
	v_bfe_u32 v25, v26, 16, 1
	v_add3_u32 v25, v26, v25, s36
	v_bfe_u32 v26, v27, 16, 1
	v_lshrrev_b32_e32 v25, 16, v25
	v_add3_u32 v26, v27, v26, s36
	v_and_or_b32 v25, v26, s37, v25
	global_store_dwordx2 v[30:31], v[24:25], off offset:512
	v_bfe_u32 v24, v20, 16, 1
	v_add3_u32 v20, v20, v24, s36
	v_bfe_u32 v24, v21, 16, 1
	v_lshrrev_b32_e32 v20, 16, v20
	v_add3_u32 v21, v21, v24, s36
	v_and_or_b32 v20, v21, s37, v20
	v_bfe_u32 v21, v22, 16, 1
	v_add3_u32 v21, v22, v21, s36
	v_bfe_u32 v22, v23, 16, 1
	v_lshrrev_b32_e32 v21, 16, v21
	v_add3_u32 v22, v23, v22, s36
	v_and_or_b32 v21, v22, s37, v21
	global_store_dwordx2 v[30:31], v[20:21], off offset:1024
	v_bfe_u32 v20, v16, 16, 1
	v_add3_u32 v16, v16, v20, s36
	v_bfe_u32 v20, v17, 16, 1
	v_lshrrev_b32_e32 v16, 16, v16
	v_add3_u32 v17, v17, v20, s36
	v_and_or_b32 v16, v17, s37, v16
	v_bfe_u32 v17, v18, 16, 1
	v_add3_u32 v17, v18, v17, s36
	v_bfe_u32 v18, v19, 16, 1
	v_lshrrev_b32_e32 v17, 16, v17
	v_add3_u32 v18, v19, v18, s36
	v_and_or_b32 v17, v18, s37, v17
	global_store_dwordx2 v[30:31], v[16:17], off offset:1536
	v_bfe_u32 v16, v12, 16, 1
	v_add3_u32 v12, v12, v16, s36
	v_bfe_u32 v16, v13, 16, 1
	v_lshrrev_b32_e32 v12, 16, v12
	v_add3_u32 v13, v13, v16, s36
	v_and_or_b32 v12, v13, s37, v12
	v_bfe_u32 v13, v14, 16, 1
	v_add3_u32 v13, v14, v13, s36
	v_bfe_u32 v14, v15, 16, 1
	v_lshrrev_b32_e32 v13, 16, v13
	v_add3_u32 v14, v15, v14, s36
	v_and_or_b32 v13, v14, s37, v13
	global_store_dwordx2 v[30:31], v[12:13], off offset:2048
	v_bfe_u32 v12, v8, 16, 1
	v_add3_u32 v8, v8, v12, s36
	v_bfe_u32 v12, v9, 16, 1
	v_lshrrev_b32_e32 v8, 16, v8
	v_add3_u32 v9, v9, v12, s36
	v_and_or_b32 v8, v9, s37, v8
	v_bfe_u32 v9, v10, 16, 1
	v_add3_u32 v9, v10, v9, s36
	v_bfe_u32 v10, v11, 16, 1
	v_lshrrev_b32_e32 v9, 16, v9
	v_add3_u32 v10, v11, v10, s36
	v_and_or_b32 v9, v10, s37, v9
	global_store_dwordx2 v[30:31], v[8:9], off offset:2560
	v_bfe_u32 v8, v4, 16, 1
	v_add3_u32 v4, v4, v8, s36
	v_bfe_u32 v8, v5, 16, 1
	v_lshrrev_b32_e32 v4, 16, v4
	v_add3_u32 v5, v5, v8, s36
	v_and_or_b32 v4, v5, s37, v4
	v_bfe_u32 v5, v6, 16, 1
	v_add3_u32 v5, v6, v5, s36
	v_bfe_u32 v6, v7, 16, 1
	v_lshrrev_b32_e32 v5, 16, v5
	v_add3_u32 v6, v7, v6, s36
	v_and_or_b32 v5, v6, s37, v5
	global_store_dwordx2 v[30:31], v[4:5], off offset:3072
	v_bfe_u32 v4, v0, 16, 1
	v_add3_u32 v0, v0, v4, s36
	v_bfe_u32 v4, v1, 16, 1
	v_lshrrev_b32_e32 v0, 16, v0
	v_add3_u32 v1, v1, v4, s36
	v_and_or_b32 v0, v1, s37, v0
	v_bfe_u32 v1, v2, 16, 1
	v_add3_u32 v1, v2, v1, s36
	v_bfe_u32 v2, v3, 16, 1
	s_add_u32 s3, s3, s10
	v_lshrrev_b32_e32 v1, 16, v1
	v_add3_u32 v2, v3, v2, s36
	s_addc_u32 s20, s20, s11
	v_and_or_b32 v1, v2, s37, v1
	v_lshl_add_u64 v[32:33], v[32:33], 0, s[14:15]
	global_store_dwordx2 v[30:31], v[0:1], off offset:3584
	s_waitcnt vmcnt(9)
	v_mul_f32_e32 v45, v93, v93
	v_mul_f32_e32 v46, v95, v95
	v_mul_f32_e32 v47, v89, v89
	v_mul_f32_e32 v48, v91, v91
	v_mul_f32_e32 v49, v85, v85
	v_mul_f32_e32 v50, v87, v87
	v_fmac_f32_e32 v45, v92, v92
	v_fmac_f32_e32 v46, v94, v94
	v_fmac_f32_e32 v47, v88, v88
	v_fmac_f32_e32 v48, v90, v90
	v_mul_f32_e32 v51, v81, v81
	v_mul_f32_e32 v52, v83, v83
	v_fmac_f32_e32 v49, v84, v84
	v_fmac_f32_e32 v50, v86, v86
	v_add_f32_e32 v45, v45, v46
	v_add_f32_e32 v46, v47, v48
	v_mul_f32_e32 v53, v77, v77
	v_mul_f32_e32 v54, v79, v79
	v_fmac_f32_e32 v51, v80, v80
	v_fmac_f32_e32 v52, v82, v82
	v_add_f32_e32 v47, v49, v50
	v_add_f32_e32 v45, v45, v46
	v_mul_f32_e32 v55, v73, v73
	v_mul_f32_e32 v56, v75, v75
	v_fmac_f32_e32 v53, v76, v76
	v_fmac_f32_e32 v54, v78, v78
	v_add_f32_e32 v48, v51, v52
	v_add_f32_e32 v45, v45, v47
	v_mul_f32_e32 v57, v69, v69
	v_mul_f32_e32 v58, v71, v71
	v_fmac_f32_e32 v55, v72, v72
	v_fmac_f32_e32 v56, v74, v74
	v_add_f32_e32 v49, v53, v54
	v_add_f32_e32 v45, v45, v48
	v_mul_f32_e32 v59, v65, v65
	v_mul_f32_e32 v60, v67, v67
	v_fmac_f32_e32 v57, v68, v68
	v_fmac_f32_e32 v58, v70, v70
	v_add_f32_e32 v50, v55, v56
	v_add_f32_e32 v45, v45, v49
	v_fmac_f32_e32 v59, v64, v64
	v_fmac_f32_e32 v60, v66, v66
	v_add_f32_e32 v51, v57, v58
	v_add_f32_e32 v45, v45, v50
	v_add_f32_e32 v45, v45, v51
	v_add_f32_e32 v46, v59, v60
	v_add_f32_e32 v45, v45, v46
	ds_bpermute_b32 v46, v38, v45
	s_waitcnt lgkmcnt(0)
	v_add_f32_e32 v45, v45, v46
	ds_bpermute_b32 v46, v39, v45
	s_waitcnt lgkmcnt(0)
	v_add_f32_e32 v45, v45, v46
	ds_bpermute_b32 v46, v40, v45
	s_waitcnt lgkmcnt(0)
	v_add_f32_e32 v45, v45, v46
	ds_bpermute_b32 v46, v41, v45
	s_waitcnt lgkmcnt(0)
	v_add_f32_e32 v45, v45, v46
	ds_bpermute_b32 v46, v42, v45
	s_waitcnt lgkmcnt(0)
	v_add_f32_e32 v45, v45, v46
	ds_bpermute_b32 v46, v43, v45
	s_and_saveexec_b64 s[18:19], s[0:1]
	s_cbranch_execz .Lmy_xp_r3
	s_waitcnt lgkmcnt(0)
	v_add_f32_e32 v45, v45, v46
	v_fmamk_f32 v45, v45, 0x3a000000, v34
	v_mul_f32_e32 v46, 0x4f800000, v45
	v_cmp_gt_f32_e32 vcc, s21, v45
	s_nop 1
	v_cndmask_b32_e32 v45, v45, v46, vcc
	v_sqrt_f32_e32 v46, v45
	s_nop 0
	v_add_u32_e32 v47, -1, v46
	v_fma_f32 v49, -v47, v46, v45
	v_add_u32_e32 v48, 1, v46
	v_cmp_ge_f32_e64 s[4:5], 0, v49
	s_nop 1
	v_cndmask_b32_e64 v47, v46, v47, s[4:5]
	v_fma_f32 v46, -v48, v46, v45
	v_cmp_lt_f32_e64 s[4:5], 0, v46
	s_nop 1
	v_cndmask_b32_e64 v46, v47, v48, s[4:5]
	v_mul_f32_e32 v47, 0x37800000, v46
	v_cndmask_b32_e32 v46, v46, v47, vcc
	v_cmp_class_f32_e32 vcc, v45, v44
	s_nop 1
	v_cndmask_b32_e32 v45, v46, v45, vcc
	v_div_scale_f32 v46, s[4:5], v45, v45, 1.0
	v_rcp_f32_e32 v47, v46
	s_add_u32 s4, s26, s3
	s_addc_u32 s5, s27, s20
	v_fma_f32 v48, -v46, v47, 1.0
	v_fmac_f32_e32 v47, v48, v47
	v_div_scale_f32 v48, vcc, 1.0, v45, 1.0
	v_mul_f32_e32 v49, v48, v47
	v_fma_f32 v50, -v46, v49, v48
	v_fmac_f32_e32 v49, v50, v47
	v_fma_f32 v46, -v46, v49, v48
	v_div_fmas_f32 v46, v46, v47, v49
	v_div_fixup_f32 v45, v46, v45, 1.0
	global_store_dword v35, v45, s[4:5]
.Lmy_xp_r3:
	s_or_b64 exec, exec, s[18:19]
	v_bfe_u32 v45, v92, 16, 1
	v_add3_u32 v92, v92, v45, s36
	v_bfe_u32 v45, v93, 16, 1
	v_lshrrev_b32_e32 v92, 16, v92
	v_add3_u32 v93, v93, v45, s36
	v_and_or_b32 v92, v93, s37, v92
	v_bfe_u32 v93, v94, 16, 1
	v_add3_u32 v93, v94, v93, s36
	v_bfe_u32 v94, v95, 16, 1
	s_waitcnt lgkmcnt(0)
	v_lshl_add_u64 v[46:47], s[26:27], 0, v[32:33]
	v_lshrrev_b32_e32 v93, 16, v93
	v_add3_u32 v94, v95, v94, s36
	v_and_or_b32 v93, v94, s37, v93
	v_add_co_u32_e32 v94, vcc, 0x6400000, v46
	s_add_i32 s62, s62, s64
	s_nop 0
	v_addc_co_u32_e32 v95, vcc, 0, v47, vcc
	global_store_dwordx2 v[94:95], v[92:93], off
	v_bfe_u32 v92, v88, 16, 1
	v_add3_u32 v88, v88, v92, s36
	v_bfe_u32 v92, v89, 16, 1
	v_lshrrev_b32_e32 v88, 16, v88
	v_add3_u32 v89, v89, v92, s36
	v_and_or_b32 v88, v89, s37, v88
	v_bfe_u32 v89, v90, 16, 1
	v_add3_u32 v89, v90, v89, s36
	v_bfe_u32 v90, v91, 16, 1
	v_lshrrev_b32_e32 v89, 16, v89
	v_add3_u32 v90, v91, v90, s36
	v_and_or_b32 v89, v90, s37, v89
	global_store_dwordx2 v[94:95], v[88:89], off offset:512
	v_bfe_u32 v88, v84, 16, 1
	v_add3_u32 v84, v84, v88, s36
	v_bfe_u32 v88, v85, 16, 1
	v_lshrrev_b32_e32 v84, 16, v84
	v_add3_u32 v85, v85, v88, s36
	v_and_or_b32 v84, v85, s37, v84
	v_bfe_u32 v85, v86, 16, 1
	v_add3_u32 v85, v86, v85, s36
	v_bfe_u32 v86, v87, 16, 1
	v_lshrrev_b32_e32 v85, 16, v85
	v_add3_u32 v86, v87, v86, s36
	v_and_or_b32 v85, v86, s37, v85
	global_store_dwordx2 v[94:95], v[84:85], off offset:1024
	v_bfe_u32 v84, v80, 16, 1
	v_add3_u32 v80, v80, v84, s36
	v_bfe_u32 v84, v81, 16, 1
	v_lshrrev_b32_e32 v80, 16, v80
	v_add3_u32 v81, v81, v84, s36
	v_and_or_b32 v80, v81, s37, v80
	v_bfe_u32 v81, v82, 16, 1
	v_add3_u32 v81, v82, v81, s36
	v_bfe_u32 v82, v83, 16, 1
	v_lshrrev_b32_e32 v81, 16, v81
	v_add3_u32 v82, v83, v82, s36
	v_and_or_b32 v81, v82, s37, v81
	global_store_dwordx2 v[94:95], v[80:81], off offset:1536
	v_bfe_u32 v80, v76, 16, 1
	v_add3_u32 v76, v76, v80, s36
	v_bfe_u32 v80, v77, 16, 1
	v_lshrrev_b32_e32 v76, 16, v76
	v_add3_u32 v77, v77, v80, s36
	v_and_or_b32 v76, v77, s37, v76
	v_bfe_u32 v77, v78, 16, 1
	v_add3_u32 v77, v78, v77, s36
	v_bfe_u32 v78, v79, 16, 1
	v_lshrrev_b32_e32 v77, 16, v77
	v_add3_u32 v78, v79, v78, s36
	v_and_or_b32 v77, v78, s37, v77
	global_store_dwordx2 v[94:95], v[76:77], off offset:2048
	v_bfe_u32 v76, v72, 16, 1
	v_add3_u32 v72, v72, v76, s36
	v_bfe_u32 v76, v73, 16, 1
	v_lshrrev_b32_e32 v72, 16, v72
	v_add3_u32 v73, v73, v76, s36
	v_and_or_b32 v72, v73, s37, v72
	v_bfe_u32 v73, v74, 16, 1
	v_add3_u32 v73, v74, v73, s36
	v_bfe_u32 v74, v75, 16, 1
	v_lshrrev_b32_e32 v73, 16, v73
	v_add3_u32 v74, v75, v74, s36
	v_and_or_b32 v73, v74, s37, v73
	global_store_dwordx2 v[94:95], v[72:73], off offset:2560
	v_bfe_u32 v72, v68, 16, 1
	v_add3_u32 v68, v68, v72, s36
	v_bfe_u32 v72, v69, 16, 1
	v_lshrrev_b32_e32 v68, 16, v68
	v_add3_u32 v69, v69, v72, s36
	v_and_or_b32 v68, v69, s37, v68
	v_bfe_u32 v69, v70, 16, 1
	v_add3_u32 v69, v70, v69, s36
	v_bfe_u32 v70, v71, 16, 1
	v_lshrrev_b32_e32 v69, 16, v69
	v_add3_u32 v70, v71, v70, s36
	v_and_or_b32 v69, v70, s37, v69
	global_store_dwordx2 v[94:95], v[68:69], off offset:3072
	v_bfe_u32 v68, v64, 16, 1
	v_add3_u32 v64, v64, v68, s36
	v_bfe_u32 v68, v65, 16, 1
	v_lshrrev_b32_e32 v64, 16, v64
	v_add3_u32 v65, v65, v68, s36
	v_and_or_b32 v64, v65, s37, v64
	v_bfe_u32 v65, v66, 16, 1
	v_add3_u32 v65, v66, v65, s36
	v_bfe_u32 v66, v67, 16, 1
	s_add_u32 s3, s3, s10
	v_lshrrev_b32_e32 v65, 16, v65
	v_add3_u32 v66, v67, v66, s36
	s_addc_u32 s20, s20, s11
	v_and_or_b32 v65, v66, s37, v65
	v_lshl_add_u64 v[32:33], v[32:33], 0, s[14:15]
	global_store_dwordx2 v[94:95], v[64:65], off offset:3584
	s_branch .LBB0_253
	s_branch .LBB0_251
